# speedup vs baseline: 1.0131x; 1.0033x over previous
; #define LBAR() asm volatile("s_waitcnt lgkmcnt(0)\n\ts_barrier" ::: "memory")
; #define MFMA16(a, b, c) __builtin_amdgcn_mfma_f32_16x16x32_bf16((a), (b), (c), 0, 0, 0)
; #define R2_BLOAD(slot, q) do { _Pragma("unroll") for (int ct = 0; ct < R2_NCT; ++ct) bq[slot][ct] = ((q) < 8) ? *(const bf16x8*)(ST + (ct * 16 + r16) * 264 + (q) * 32 + g4 * 8) : *(const bf16x8*)(VT + (ct * 16 + r16) * 136 + ((q) - 8) * 32 + g4 * 8); } while (0)
; __global__ void __launch_bounds__(512, 2) fwd_megakernel(Params kp_) {
;     ...
;                                 bf16* ST = ST0 + (n & 1) * (R2_NCT * 16 * 264); bf16* STn = ST0 + ((n + 1) & 1) * (R2_NCT * 16 * 264); bf16* VT = VT0 + (n & 1) * (R2_NCT * 16 * 136);
; #pragma unroll
;                                 for (int it = 0; it < R2_NCT / 2; ++it) { const int idx_ = tid + 512 * it, i = idx_ >> 2, c8 = idx_ & 3; const u32x4 w = vreg[it];
; #pragma unroll
;                                     for (int e = 0; e < 4; ++e) { VT[(c8 * 8 + 2 * e) * 136 + i] = (bf16)(w[e] & 0xffffu); VT[(c8 * 8 + 2 * e + 1) * 136 + i] = (bf16)(w[e] >> 16); } }
;                                 LBAR();
;                                 f32x4 acc[R2_NCT];
; #pragma unroll
;                                 for (int ct = 0; ct < R2_NCT; ++ct) acc[ct] = (f32x4){0.f, 0.f, 0.f, 0.f};
;                                 {
;                                     bf16x8 bq[3][R2_NCT];
;     ...
;                                     R2_BLOAD(0, 0); R2_BLOAD(1, 1);
; #pragma unroll
;                                     for (int q = 0; q < 12; ++q) {
;                                         if (q + 2 < 12) R2_BLOAD((q + 2) % 3, q + 2);
;                                         __builtin_amdgcn_sched_barrier(0);
; #pragma unroll
;                                         for (int ct = 0; ct < R2_NCT; ++ct) acc[ct] = MFMA16(bq[q % 3][ct], afr[q], acc[ct]);
;                                         __builtin_amdgcn_sched_barrier(0);
;                                     }
;     ...
;                                 }
.LBB0_558:
	s_and_b32 s1, s0, 1
	s_mul_i32 s4, s1, 0x2200
	s_add_i32 s11, s4, 0
	s_lshl_b32 s1, s1, 13
	v_lshlrev_b32_e32 v115, 1, v104
	s_add_i32 s1, s11, s1
	v_add3_u32 v131, s11, v115, v103
	v_add3_u32 v115, s11, v103, v115
	s_waitcnt vmcnt(8)
	ds_write_b16 v131, v84 offset:33792
	ds_write_b16_d16_hi v115, v84 offset:34064
	ds_write_b16 v131, v85 offset:34336
	ds_write_b16_d16_hi v115, v85 offset:34608
	ds_write_b16 v131, v86 offset:34880
	ds_write_b16_d16_hi v115, v86 offset:35152
	ds_write_b16 v131, v87 offset:35424
	ds_write_b16_d16_hi v115, v87 offset:35696
	v_add_u32_e32 v115, s1, v196
	s_waitcnt lgkmcnt(0)
	s_barrier
	v_add_u32_e32 v131, v115, v124
	ds_read_b128 v[84:87], v131
	ds_read_b128 v[132:135], v131 offset:8448
	v_add3_u32 v131, s1, v124, v196
	v_add_u32_e32 v115, v115, v125
	ds_read_b128 v[136:139], v131 offset:64
	ds_read_b128 v[140:143], v131 offset:128
	ds_read_b128 v[144:147], v115 offset:64
	ds_read_b128 v[148:151], v115 offset:128
	s_add_i32 s9, s0, 1
	s_and_b32 s10, 1, s9
	s_add_u32 s4, s6, 0x80
	s_addc_u32 s5, s7, 0
	s_cmp_eq_u32 s0, 63
	s_cselect_b32 s0, s6, s4
	s_cselect_b32 s6, 0x1f8000, s8
	s_cselect_b32 s1, s7, s5
	s_cmp_eq_u32 s10, 1
	s_waitcnt lgkmcnt(5)
	v_mfma_f32_16x16x32_bf16 v[84:87], v[84:87], v[60:63], 0
	s_waitcnt lgkmcnt(4)
	v_mfma_f32_16x16x32_bf16 v[60:63], v[132:135], v[60:63], 0
	ds_read_b128 v[132:135], v131 offset:192
	ds_read_b128 v[152:155], v115 offset:192
	s_waitcnt lgkmcnt(5)
	v_mfma_f32_16x16x32_bf16 v[84:87], v[136:139], v[40:43], v[84:87]
	s_waitcnt lgkmcnt(3)
	v_mfma_f32_16x16x32_bf16 v[40:43], v[144:147], v[40:43], v[60:63]
	s_nop 2
	ds_read_b128 v[60:63], v131 offset:256
	ds_read_b128 v[136:139], v115 offset:256
	v_mfma_f32_16x16x32_bf16 v[84:87], v[140:143], v[36:39], v[84:87]
	s_waitcnt lgkmcnt(4)
	v_mfma_f32_16x16x32_bf16 v[36:39], v[148:151], v[36:39], v[40:43]
	s_nop 2
	ds_read_b128 v[40:43], v131 offset:320
	ds_read_b128 v[140:143], v115 offset:320
	s_waitcnt lgkmcnt(5)
	v_mfma_f32_16x16x32_bf16 v[84:87], v[132:135], v[32:35], v[84:87]
	s_waitcnt lgkmcnt(4)
	v_mfma_f32_16x16x32_bf16 v[32:35], v[152:155], v[32:35], v[36:39]
	s_nop 2
	ds_read_b128 v[36:39], v131 offset:384
	ds_read_b128 v[132:135], v115 offset:384
	s_waitcnt lgkmcnt(5)
	v_mfma_f32_16x16x32_bf16 v[60:63], v[60:63], v[28:31], v[84:87]
	s_waitcnt lgkmcnt(4)
	v_mfma_f32_16x16x32_bf16 v[28:31], v[136:139], v[28:31], v[32:35]
	s_nop 2
	ds_read_b128 v[32:35], v131 offset:448
	ds_read_b128 v[84:87], v115 offset:448
	s_waitcnt lgkmcnt(5)
	v_mfma_f32_16x16x32_bf16 v[40:43], v[40:43], v[24:27], v[60:63]
	s_waitcnt lgkmcnt(4)
	v_mfma_f32_16x16x32_bf16 v[24:27], v[140:143], v[24:27], v[28:31]
	v_add3_u32 v115, s11, v126, v196
	v_add_u32_e32 v131, s11, v196
	v_add_u32_e32 v136, v131, v127
	ds_read_b128 v[28:31], v115 offset:33792
	ds_read_b128 v[60:63], v136 offset:33792
	s_waitcnt lgkmcnt(5)
	v_mfma_f32_16x16x32_bf16 v[36:39], v[36:39], v[20:23], v[40:43]
	s_waitcnt lgkmcnt(4)
	v_mfma_f32_16x16x32_bf16 v[20:23], v[132:135], v[20:23], v[24:27]
	s_nop 2
	ds_read_b128 v[24:27], v115 offset:33856
	ds_read_b128 v[40:43], v136 offset:33856
	s_waitcnt lgkmcnt(5)
	v_mfma_f32_16x16x32_bf16 v[32:35], v[32:35], v[16:19], v[36:39]
	s_waitcnt lgkmcnt(4)
	v_mfma_f32_16x16x32_bf16 v[16:19], v[84:87], v[16:19], v[20:23]
	s_nop 2
	ds_read_b128 v[20:23], v115 offset:33920
	ds_read_b128 v[36:39], v136 offset:33920
	s_waitcnt lgkmcnt(5)
	v_mfma_f32_16x16x32_bf16 v[28:31], v[28:31], v[12:15], v[32:35]
	s_waitcnt lgkmcnt(4)
	v_mfma_f32_16x16x32_bf16 v[12:15], v[60:63], v[12:15], v[16:19]
	s_nop 2
	ds_read_b128 v[16:19], v115 offset:33984
	ds_read_b128 v[32:35], v136 offset:33984
	s_waitcnt lgkmcnt(5)
	v_mfma_f32_16x16x32_bf16 v[24:27], v[24:27], v[8:11], v[28:31]
	s_waitcnt lgkmcnt(4)
	v_mfma_f32_16x16x32_bf16 v[8:11], v[40:43], v[8:11], v[12:15]
	s_waitcnt lgkmcnt(3)
	v_mfma_f32_16x16x32_bf16 v[12:15], v[20:23], v[4:7], v[24:27]
	s_waitcnt lgkmcnt(2)
	v_mfma_f32_16x16x32_bf16 v[4:7], v[36:39], v[4:7], v[8:11]
	s_waitcnt lgkmcnt(1)
	v_mfma_f32_16x16x32_bf16 v[132:135], v[16:19], v[0:3], v[12:15]
	s_waitcnt lgkmcnt(0)
; __device__ __forceinline__ unsigned pk2(float lo, float hi) { const f32x2_t v = {lo, hi}; const bf16x2_t b = __builtin_convertvector(v, bf16x2_t); return __builtin_bit_cast(unsigned, b); }
; __global__ void __launch_bounds__(512, 2) fwd_megakernel(Params kp_) {
;     ...
;                                 { const size_t rown = (n < 63) ? row0 + 128 : row0; R2_LOAD_A(rown); }
; #pragma unroll
;                                 for (int ct = 0; ct < R2_NCT; ++ct) { bf16* op = (rep_ + 1 < REP_R2) ? (dmy + (wave * 16 + r16) * 64 + ct * 16 + g4 * 4) : (proj + (row0 + wave * 16 + r16) * RETP + 2048 + h * 512 + e0 + ct * 16 + g4 * 4);
;                                     u32x2 w; w.x = pk2(acc[ct][0], acc[ct][1]); w.y = pk2(acc[ct][2], acc[ct][3]); *(u32x2*)op = w; }
; #pragma unroll
;                                 for (int a = 0; a < R2_NCT; ++a) { Sacc[a][0] = Sacc[a][0] * gam; Sacc[a][1] = Sacc[a][1] * gam; }
;                                 {
;                                     bf16x8 vq[2][R2_NCT];
; #pragma unroll
;                                     for (int dt = 0; dt < R2_NCT; ++dt) vq[0][dt] = *(const bf16x8*)(VT + (dt * 16 + r16) * 136 + g4 * 8);
; #pragma unroll
;                                     for (int q = 0; q < 4; ++q) {
;                                         if (q + 1 < 4) {
; #pragma unroll
;                                             for (int dt = 0; dt < R2_NCT; ++dt) vq[(q + 1) & 1][dt] = *(const bf16x8*)(VT + (dt * 16 + r16) * 136 + (q + 1) * 32 + g4 * 8); }
;                                         __builtin_amdgcn_sched_barrier(0);
; #pragma unroll
;                                         for (int dt = 0; dt < R2_NCT; ++dt) { Sacc[dt][0] = MFMA16(vq[q & 1][dt], kfr[2 * q], Sacc[dt][0]); Sacc[dt][1] = MFMA16(vq[q & 1][dt], kfr[2 * q + 1], Sacc[dt][1]); }
;                                         __builtin_amdgcn_sched_barrier(0);
;                                     }
;                                 }
;                                 R2_LOAD_K(n < 63 ? n + 1 : n);
; #pragma unroll
;                                 for (int dt = 0; dt < R2_NCT; ++dt)
; #pragma unroll
;                                     for (int kt = 0; kt < 2; ++kt)
; #pragma unroll
;                                         for (int j = 0; j < 4; ++j) STn[(dt * 16 + g4 * 4 + j) * 264 + (2 * wave + kt) * 16 + r16] = (bf16)f2bf(Sacc[dt][kt][j]);
	v_mfma_f32_16x16x32_bf16 v[136:139], v[32:35], v[0:3], v[4:7]
	v_lshl_add_u64 v[0:1], s[0:1], 0, v[172:173]
	v_mad_u64_u32 v[2:3], s[10:11], v0, s69, v[180:181]
	v_mov_b32_e32 v0, v3
	v_mad_u64_u32 v[0:1], s[10:11], v1, s69, v[0:1]
	v_mov_b32_e32 v3, v0
	global_load_dwordx4 v[60:63], v[2:3], off
	global_load_dwordx4 v[12:15], v[2:3], off offset:2048
	v_lshl_add_u64 v[176:177], v[2:3], 0, v[170:171]
	global_load_dwordx4 v[40:43], v[176:177], off
	v_mov_b32_e32 v8, 0
	v_mov_b32_e32 v9, 0
	v_mov_b32_e32 v10, 0
	v_mov_b32_e32 v11, 0
	v_cmp_le_u32_e32 vcc, 0x80, v199
	s_mov_b64 exec, vcc
	global_load_dwordx4 v[8:11], v[176:177], off offset:2048
	s_mov_b64 exec, -1
	v_lshl_add_u64 v[176:177], v[176:177], 0, v[170:171]
	global_load_dwordx4 v[36:39], v[176:177], off
	v_mov_b32_e32 v4, 0
	v_mov_b32_e32 v5, 0
	v_mov_b32_e32 v6, 0
	v_mov_b32_e32 v7, 0
	v_cmp_le_u32_e32 vcc, 0x100, v199
	s_mov_b64 exec, vcc
	global_load_dwordx4 v[4:7], v[176:177], off offset:2048
	s_mov_b64 exec, -1
	v_lshl_add_u64 v[176:177], v[176:177], 0, v[170:171]
	global_load_dwordx4 v[32:35], v[176:177], off
	v_mov_b32_e32 v0, 0
	v_mov_b32_e32 v1, 0
	v_mov_b32_e32 v2, 0
	v_mov_b32_e32 v3, 0
	v_cmp_le_u32_e32 vcc, 0x180, v199
	s_mov_b64 exec, vcc
	global_load_dwordx4 v[0:3], v[176:177], off offset:2048
	s_mov_b64 exec, -1
	v_lshl_add_u64 v[176:177], v[176:177], 0, v[170:171]
	global_load_dwordx4 v[28:31], v[176:177], off
	v_lshl_add_u64 v[176:177], v[176:177], 0, v[170:171]
	global_load_dwordx4 v[24:27], v[176:177], off
	v_lshl_add_u64 v[176:177], v[176:177], 0, v[170:171]
	global_load_dwordx4 v[20:23], v[176:177], off
	v_lshl_add_u64 v[176:177], v[176:177], 0, v[170:171]
	global_load_dwordx4 v[16:19], v[176:177], off
	v_lshl_add_u64 v[84:85], s[0:1], 0, v[104:105]
	v_mov_b64_e32 v[86:87], s[52:53]
	v_mad_u64_u32 v[86:87], s[0:1], v84, s69, v[86:87]
	v_mov_b32_e32 v84, v87
	v_mad_u64_u32 v[84:85], s[0:1], v85, s69, v[84:85]
	v_mov_b32_e32 v87, v84
	v_lshl_add_u64 v[84:85], v[86:87], 0, s[94:95]
	v_lshl_add_u64 v[84:85], s[2:3], 1, v[84:85]
	v_lshl_add_u64 v[84:85], v[84:85], 0, v[112:113]
	v_add_co_u32_e64 v84, s[0:1], s64, v84
	v_cvt_pk_bf16_f32 v132, v132, v133
	s_nop 0
	v_addc_co_u32_e64 v85, s[0:1], 0, v85, s[0:1]
	global_load_dwordx4 v[84:87], v[84:85], off
	v_cvt_pk_bf16_f32 v133, v134, v135
	global_store_dwordx2 v[122:123], v[132:133], off offset:-32
	v_cvt_pk_bf16_f32 v132, v136, v137
	v_cvt_pk_bf16_f32 v133, v138, v139
	v_mov_b32_e32 v115, v114
	global_store_dwordx2 v[122:123], v[132:133], off
	v_pk_mul_f32 v[98:99], v[114:115], v[98:99]
	v_pk_mul_f32 v[94:95], v[114:115], v[94:95]
	v_pk_mul_f32 v[90:91], v[114:115], v[90:91]
	v_pk_mul_f32 v[82:83], v[114:115], v[82:83]
	v_add_u32_e32 v115, v131, v126
	ds_read_b128 v[132:135], v115 offset:33792
	ds_read_b128 v[136:139], v115 offset:38144
	ds_read_b128 v[140:143], v115 offset:33856
	ds_read_b128 v[144:147], v115 offset:38208
	v_pk_mul_f32 v[96:97], v[120:121], v[96:97]
	v_pk_mul_f32 v[92:93], v[120:121], v[92:93]
	v_pk_mul_f32 v[88:89], v[120:121], v[88:89]
	v_pk_mul_f32 v[80:81], v[120:121], v[80:81]
	s_waitcnt vmcnt(22) lgkmcnt(3)
	v_mfma_f32_16x16x32_bf16 v[96:99], v[132:135], v[52:55], v[96:99]
	s_waitcnt vmcnt(16)
	v_mfma_f32_16x16x32_bf16 v[92:95], v[132:135], v[76:79], v[92:95]
	s_waitcnt lgkmcnt(2)
	v_mfma_f32_16x16x32_bf16 v[52:55], v[136:139], v[52:55], v[88:91]
	v_mfma_f32_16x16x32_bf16 v[76:79], v[136:139], v[76:79], v[80:83]
	s_nop 2
	ds_read_b128 v[80:83], v115 offset:33920
	ds_read_b128 v[88:91], v115 offset:38272
	s_waitcnt vmcnt(20) lgkmcnt(3)
	v_mfma_f32_16x16x32_bf16 v[96:99], v[140:143], v[68:71], v[96:99]
	s_waitcnt vmcnt(18)
	v_mfma_f32_16x16x32_bf16 v[92:95], v[140:143], v[72:75], v[92:95]
	s_waitcnt lgkmcnt(2)
	v_mfma_f32_16x16x32_bf16 v[52:55], v[144:147], v[68:71], v[52:55]
	v_mfma_f32_16x16x32_bf16 v[68:71], v[144:147], v[72:75], v[76:79]
	ds_read_b128 v[72:75], v115 offset:33984
	s_nop 1
	ds_read_b128 v[76:79], v115 offset:38336
	s_waitcnt lgkmcnt(3)
	v_mfma_f32_16x16x32_bf16 v[96:99], v[80:83], v[48:51], v[96:99]
	s_waitcnt vmcnt(16)
	v_mfma_f32_16x16x32_bf16 v[80:83], v[80:83], v[64:67], v[92:95]
	s_waitcnt lgkmcnt(2)
	v_mfma_f32_16x16x32_bf16 v[48:51], v[88:91], v[48:51], v[52:55]
	v_mfma_f32_16x16x32_bf16 v[52:55], v[88:91], v[64:67], v[68:71]
	s_waitcnt lgkmcnt(1)
	v_mfma_f32_16x16x32_bf16 v[96:99], v[72:75], v[44:47], v[96:99]
	s_waitcnt vmcnt(15)
	v_mfma_f32_16x16x32_bf16 v[92:95], v[72:75], v[56:59], v[80:83]
	s_waitcnt lgkmcnt(0)
	v_mfma_f32_16x16x32_bf16 v[88:91], v[76:79], v[44:47], v[48:51]
	v_mfma_f32_16x16x32_bf16 v[80:83], v[76:79], v[56:59], v[52:55]
	s_mov_b32 s7, s95
	v_lshl_add_u64 v[44:45], s[6:7], 1, v[116:117]
	s_nop 0
	v_add_co_u32_e64 v58, s[0:1], s64, v44
	v_lshl_add_u64 v[56:57], v[44:45], 0, s[90:91]
	s_nop 0
	v_addc_co_u32_e64 v59, s[0:1], 0, v45, s[0:1]
	global_load_dwordx4 v[52:55], v[44:45], off
	global_load_dwordx4 v[68:71], v[44:45], off offset:1024
	global_load_dwordx4 v[72:75], v[56:57], off offset:1024
	global_load_dwordx4 v[64:67], v[56:57], off offset:2048
	global_load_dwordx4 v[48:51], v[44:45], off offset:2048
	s_nop 0
	global_load_dwordx4 v[44:47], v[44:45], off offset:3072
	s_nop 0
	global_load_dwordx4 v[76:79], v[58:59], off
	s_nop 0
	global_load_dwordx4 v[56:59], v[56:57], off offset:3072
	s_cselect_b32 s0, 0x4200, 0
	v_cvt_pk_bf16_f32 v115, v96, s0
	v_add_u32_e32 v131, s0, v128
	ds_write_b16 v131, v115
	v_cvt_pk_bf16_f32 v115, v97, s0
	ds_write_b16 v131, v115 offset:528
	v_cvt_pk_bf16_f32 v115, v98, s0
	ds_write_b16 v131, v115 offset:1056
	v_cvt_pk_bf16_f32 v115, v99, s0
	ds_write_b16 v131, v115 offset:1584
	v_cvt_pk_bf16_f32 v115, v92, s0
	ds_write_b16 v131, v115 offset:32
	v_cvt_pk_bf16_f32 v115, v93, s0
	ds_write_b16 v131, v115 offset:560
	v_cvt_pk_bf16_f32 v115, v94, s0
	ds_write_b16 v131, v115 offset:1088
	v_cvt_pk_bf16_f32 v115, v95, s0
	ds_write_b16 v131, v115 offset:1616
	v_cvt_pk_bf16_f32 v115, v88, s0
	ds_write_b16 v131, v115 offset:8448
	v_cvt_pk_bf16_f32 v115, v89, s0
	ds_write_b16 v131, v115 offset:8976
	v_cvt_pk_bf16_f32 v115, v90, s0
	ds_write_b16 v131, v115 offset:9504
	v_cvt_pk_bf16_f32 v115, v91, s0
	ds_write_b16 v131, v115 offset:10032
	v_cvt_pk_bf16_f32 v115, v80, s0
	ds_write_b16 v131, v115 offset:8480
	v_cvt_pk_bf16_f32 v115, v81, s0
	ds_write_b16 v131, v115 offset:9008
	v_cvt_pk_bf16_f32 v115, v82, s0
	ds_write_b16 v131, v115 offset:9536
	v_cvt_pk_bf16_f32 v115, v83, s0
	s_add_i32 s8, s8, 0x8000
	s_mov_b64 s[0:1], 0x184000
	v_lshl_add_u64 v[122:123], v[122:123], 0, s[0:1]
	s_cmp_eq_u32 s9, 64
	s_mov_b64 s[6:7], s[4:5]
	s_mov_b32 s0, s9
	ds_write_b16 v131, v115 offset:10064
	s_cbranch_scc0 .LBB0_558
	v_readlane_b32 s0, v254, 14
	s_add_i32 s17, s17, s88
	s_add_i32 s16, s16, s0
	s_cmpk_gt_i32 s17, 0xff
	s_cbranch_scc0 .LBB0_554
